# PA epilogue of dk/dv tiles (pn 2..5) delayed by 3 x s_sleep 127 to de-phase their store burst
# speedup vs baseline: 1.0079x; 1.0018x over previous
.LBB0_392:
	s_cmp_lt_u32 s72, 2
	s_cbranch_scc1 .Lpd_skip
	s_cmp_gt_u32 s72, 5
	s_cbranch_scc1 .Lpd_skip
	s_sleep 127
	s_sleep 127
	s_sleep 127
